# scan items of one (b,h) placed on one XCD (shared Mp chunks served by L2)
# speedup vs baseline: 1.1061x; 1.0020x over previous
.LBB0_997:
	s_or_b64 exec, exec, s[0:1]
	s_waitcnt lgkmcnt(0)
	v_mov_b32_e32 v0, v174
	s_cmpk_gt_i32 s90, 0xff
	s_barrier
	s_cbranch_scc1 .LBB0_1034
	s_mov_b32 s73, s90
	s_cmp_lg_u32 s88, 0x100
	s_cbranch_scc1 .Lscan_noremap
	s_and_b32 s73, s90, 7
	s_lshl_b32 s73, s73, 5
	s_lshr_b32 s2, s90, 3
	s_or_b32 s73, s73, s2
.Lscan_noremap:
	s_lshl_b32 s2, s73, 10
	s_lshl_b32 s3, s88, 10
	v_mov_b32_e32 v73, 0
	s_movk_i32 s10, 0x2000
	s_movk_i32 s11, 0x4000
	s_movk_i32 s33, 0x6000
	s_mov_b32 s34, 0xa000
	s_movk_i32 s35, 0x300
	s_movk_i32 s38, 0x100
	s_movk_i32 s39, 0x5f
	s_movk_i32 s40, 0x60
	s_movk_i32 s41, 0x90
	s_movk_i32 s68, 0x2e00
	s_mov_b32 s69, 0x78000
	s_mov_b32 s70, 0x7a000
	s_mov_b32 s71, 0x7c000
	s_mov_b64 s[12:13], 0x7e000
	s_mov_b32 s72, 0x7e000
	s_branch .LBB0_1000
